# v81 + waves 0-3 loop copies: DMA destination / priority setup moved in front of the tile barrier so the first K/V DMA issues immediately behind it
# baseline (speedup 1.0000x reference)
; #define SBAR() __builtin_amdgcn_sched_barrier(0)
; #define ATT_DMA_K(t) do { const bf16_t* kg_ = Kh + (size_t)(t) * 64 * LDK; LAS unsigned char* sb_ = lds + ((t) & 3) * KBUF; \
;     _Pragma("unroll") for (int i_ = 0; i_ < NKP; ++i_) __builtin_amdgcn_global_load_lds((const unsigned*)(kg_ + kgo[i_]), (LAS unsigned*)(sb_ + (wid + 8 * i_) * 1024), 16, 0, 0); } while (0)
; #define ATT_DMA_V(t, vs) do { const bf16_t* vg_ = Vh + (size_t)(t) * 64 * LDV; LAS unsigned char* sb_ = lds + V_OFF + (vs) * SHM_V; \
;     _Pragma("unroll") for (int i_ = 0; i_ < 2; ++i_) __builtin_amdgcn_global_load_lds((const unsigned*)(vg_ + vgo[i_]), (LAS unsigned*)(sb_ + (2 * wid + i_) * 1024), 16, 0, 0); } while (0)
; #define ATT_SEG(t) do { if constexpr (MODE != 0) { if (((t) == tL && tL > 0) || (t) == tR) { const float f_ = (t) == tR ? fR : fL; l_reg *= f_; \
;     _Pragma("unroll") for (int d = 0; d < 4; ++d) _Pragma("unroll") for (int r = 0; r < 16; ++r) o[d][r] *= f_; } } } while (0)
; #define ATT_TOP(N) do { asm volatile("s_waitcnt vmcnt(%0)" :: "n"(N) : "memory"); __builtin_amdgcn_s_barrier(); asm volatile("" ::: "memory"); } while (0)
; template <int DQK, int MODE, int LDQ, int LDK, int LDV> ...
;     ...
;     for (int j = 0; j < NT; ++j) {
;         if (j + 2 < NT) ATT_TOP(NKP + 2); else ATT_TOP(0);
;         if (j + 3 < NT) ATT_DMA_K(j + 3);
;         if (j + 2 < NT) ATT_DMA_V(j + 2, v2);
;         ATT_SEG(j); SBAR();
.LBB0_1920:
	s_and_b32 s1, s22, 0x6000
	s_add_i32 m0, s59, s1
	s_lshl_b32 s1, s96, 14
	s_add_i32 s1, s95, s1
	s_setprio 0
	s_waitcnt vmcnt(3)
	s_barrier
	global_load_lds_dwordx4 v100, s[34:35]
	s_add_i32 s2, s1, 0x400
	s_mov_b32 m0, s1
	s_sub_i32 s74, s0, s98
	global_load_lds_dwordx4 v102, s[34:35]
	s_mov_b32 m0, s2
	s_cmp_le_u32 s74, s101
	global_load_lds_dwordx4 v104, s[34:35]
	s_mov_b32 s1, s23
	s_cbranch_scc1 .Ldt_d0_resc

; #define SBAR() __builtin_amdgcn_sched_barrier(0)
; #define ATT_DMA_K(t) do { const bf16_t* kg_ = Kh + (size_t)(t) * 64 * LDK; LAS unsigned char* sb_ = lds + ((t) & 3) * KBUF; \
;     _Pragma("unroll") for (int i_ = 0; i_ < NKP; ++i_) __builtin_amdgcn_global_load_lds((const unsigned*)(kg_ + kgo[i_]), (LAS unsigned*)(sb_ + (wid + 8 * i_) * 1024), 16, 0, 0); } while (0)
; #define ATT_DMA_V(t, vs) do { const bf16_t* vg_ = Vh + (size_t)(t) * 64 * LDV; LAS unsigned char* sb_ = lds + V_OFF + (vs) * SHM_V; \
;     _Pragma("unroll") for (int i_ = 0; i_ < 2; ++i_) __builtin_amdgcn_global_load_lds((const unsigned*)(vg_ + vgo[i_]), (LAS unsigned*)(sb_ + (2 * wid + i_) * 1024), 16, 0, 0); } while (0)
; #define ATT_SEG(t) do { if constexpr (MODE != 0) { if (((t) == tL && tL > 0) || (t) == tR) { const float f_ = (t) == tR ? fR : fL; l_reg *= f_; \
;     _Pragma("unroll") for (int d = 0; d < 4; ++d) _Pragma("unroll") for (int r = 0; r < 16; ++r) o[d][r] *= f_; } } } while (0)
; #define ATT_TOP(N) do { asm volatile("s_waitcnt vmcnt(%0)" :: "n"(N) : "memory"); __builtin_amdgcn_s_barrier(); asm volatile("" ::: "memory"); } while (0)
; template <int DQK, int MODE, int LDQ, int LDK, int LDV> ...
;     ...
;     for (int j = 0; j < NT; ++j) {
;         if (j + 2 < NT) ATT_TOP(NKP + 2); else ATT_TOP(0);
;         if (j + 3 < NT) ATT_DMA_K(j + 3);
;         if (j + 2 < NT) ATT_DMA_V(j + 2, v2);
;         ATT_SEG(j); SBAR();
.LBB0_1951:
	s_and_b32 s2, s22, 0x6000
	s_add_i32 m0, s94, s2
	s_lshl_b32 s2, s1, 14
	s_add_i32 s2, s48, s2
	s_setprio 0
	s_waitcnt vmcnt(3)
	s_barrier
	global_load_lds_dwordx4 v100, s[34:35]
	s_add_i32 s3, s2, 0x400
	s_mov_b32 m0, s2
	s_sub_i32 s74, s0, s98
	global_load_lds_dwordx4 v102, s[34:35]
	s_mov_b32 m0, s3
	s_cmp_le_u32 s74, s101
	global_load_lds_dwordx4 v104, s[34:35]
	s_mov_b32 s23, s62
	s_cbranch_scc1 .Ldt_d1_resc

; #define LAS __attribute__((address_space(3)))
; DI void expsum(f32x16& p, float& l_reg, bf16x8& pa0, bf16x8& pa1) {
; #pragma unroll
;     for (int r = 0; r < 16; ++r) p[r] = __builtin_amdgcn_exp2f(p[r]);
;     float ps = 0.f;
; #pragma unroll
;     for (int r = 0; r < 16; ++r) ps += p[r];
;     l_reg += ps; asm volatile("" : "+v"(l_reg));
;     ...
;     ATT_PK4(p, 0, pa0); ATT_PK4(p, 8, pa1);
;     ...
; }
; DI int v_rd_base(int lane) { return ((lane & 3) << 3) | (((lane >> 2) & 3) << 6) | (((lane >> 4) & 1) << 5) | (((lane >> 5) & 1) << 8); }
; template <int OFF> DI s16x4 tr_read(int vb) { s16x4 r; asm volatile("ds_read_b64_tr_b16 %0, %1 offset:%2" : "=&v"(r) : "v"(vb), "i"(OFF) : "memory"); return r; }
; template <int H> DI void v_reads(s16x4* vf, int vb) {
;     vf[0] = tr_read<v_rd_off(0, 2 * H, 0)>(vb); vf[1] = tr_read<v_rd_off(0, 2 * H, 1)>(vb); vf[2] = tr_read<v_rd_off(0, 2 * H + 1, 0)>(vb); vf[3] = tr_read<v_rd_off(0, 2 * H + 1, 1)>(vb);
;     vf[4] = tr_read<v_rd_off(1, 2 * H, 0)>(vb); vf[5] = tr_read<v_rd_off(1, 2 * H, 1)>(vb); vf[6] = tr_read<v_rd_off(1, 2 * H + 1, 0)>(vb); vf[7] = tr_read<v_rd_off(1, 2 * H + 1, 1)>(vb);
;     vf[8] = tr_read<v_rd_off(2, 2 * H, 0)>(vb); vf[9] = tr_read<v_rd_off(2, 2 * H, 1)>(vb); vf[10] = tr_read<v_rd_off(2, 2 * H + 1, 0)>(vb); vf[11] = tr_read<v_rd_off(2, 2 * H + 1, 1)>(vb);
;     vf[12] = tr_read<v_rd_off(3, 2 * H, 0)>(vb); vf[13] = tr_read<v_rd_off(3, 2 * H, 1)>(vb); vf[14] = tr_read<v_rd_off(3, 2 * H + 1, 0)>(vb); vf[15] = tr_read<v_rd_off(3, 2 * H + 1, 1)>(vb);
; }
; DI void pv_mma(f32x16* o, const s16x4* vf, bf16x8 pa0, bf16x8 pa1) {
;     ...
; #pragma unroll
;     for (int d0 = 0; d0 < 4; ++d0) {
;         o[d0] = __builtin_amdgcn_mfma_f32_32x32x16_bf16(pa0, ATT_PK(vf[4 * d0], vf[4 * d0 + 1]), o[d0], 0, 0, 0);
;         o[d0] = __builtin_amdgcn_mfma_f32_32x32x16_bf16(pa1, ATT_PK(vf[4 * d0 + 2], vf[4 * d0 + 3]), o[d0], 0, 0, 0); }
;     ...
; }
; template <int DQK, int D0A, int D0B> DI void k_reads(bf16x8* kf, const LAS unsigned char* Ks, int half, int r32, int hi) {
; #pragma unroll
;     for (int d0 = D0A; d0 < D0B; ++d0) kf[d0 - D0A] = *(const LAS bf16x8*)(Ks + half * (32 * DQK * 2) + kswz<DQK>(r32, (d0 * 16 + hi * 8) * 2));
; }
; template <int D0A, int D0B> DI void qk_mma(f32x16& p, const bf16x8* kf, const bf16x8* qr) {
; #pragma unroll
;     for (int d0 = D0A; d0 < D0B; ++d0) {
.LBB0_1982:
	s_and_b32 s1, s43, 3
	s_mulk_i32 s1, 0x6000
	s_add_i32 s1, s49, s1
	s_mov_b32 s0, s5
	s_mov_b32 s5, s44
	s_mov_b32 s44, s4
	s_lshl_b32 s4, s4, 14
	s_add_i32 s4, s52, s4
	s_add_i32 s6, s4, 0x400
	s_setprio 0
	s_mov_b32 m0, s1
	s_waitcnt vmcnt(5)
	s_barrier
	global_load_lds_dwordx4 v136, s[34:35]
	s_add_i32 m0, s1, 0x2000
	s_nop 0
	global_load_lds_dwordx4 v138, s[34:35]
	s_add_i32 m0, s1, 0x4000
	s_nop 0
	global_load_lds_dwordx4 v140, s[34:35]
	s_mov_b32 m0, s4
	s_add_i32 s1, s43, -3
	global_load_lds_dwordx4 v144, s[34:35]
	s_mov_b32 m0, s6
	s_nop 0
	global_load_lds_dwordx4 v142, s[34:35]
	s_and_b32 s1, s1, 3
	s_mulk_i32 s1, 0x6000
	v_add_u32_e32 v246, s1, v158
	v_add_u32_e32 v250, v246, v151
	v_add_u32_e32 v251, v246, v149
	v_add_u32_e32 v252, v246, v148
	v_add_u32_e32 v253, v246, v147
	s_lshl_b32 s1, s0, 14
	ds_read_b128 v[190:193], v250 offset:12416
	ds_read_b128 v[194:197], v251 offset:12416
	ds_read_b128 v[174:177], v250 offset:12288
	ds_read_b128 v[178:181], v251 offset:12288
	ds_read_b128 v[182:185], v252 offset:12288
	ds_read_b128 v[186:189], v253 offset:12288
	v_add_u32_e32 v254, s1, v130
	ds_read_b64_tr_b16 v[198:199], v254 offset:0
	ds_read_b64_tr_b16 v[200:201], v254 offset:0x800
	ds_read_b64_tr_b16 v[202:203], v254 offset:0x1000
	ds_read_b64_tr_b16 v[204:205], v254 offset:0x1800
	ds_read_b64_tr_b16 v[206:207], v254 offset:0x200
	ds_read_b64_tr_b16 v[208:209], v254 offset:0xa00
	ds_read_b64_tr_b16 v[210:211], v254 offset:0x1200
	ds_read_b64_tr_b16 v[212:213], v254 offset:0x1a00
	ds_read_b64_tr_b16 v[214:215], v254 offset:0x400
	ds_read_b64_tr_b16 v[216:217], v254 offset:0xc00
	ds_read_b64_tr_b16 v[218:219], v254 offset:0x1400
	ds_read_b64_tr_b16 v[220:221], v254 offset:0x1c00
	ds_read_b64_tr_b16 v[222:223], v254 offset:0x600
	ds_read_b64_tr_b16 v[224:225], v254 offset:0xe00
	ds_read_b64_tr_b16 v[226:227], v254 offset:0x1600
	ds_read_b64_tr_b16 v[228:229], v254 offset:0x1e00
	s_setprio 1
	v_exp_f32_e32 v64, v64
	v_exp_f32_e32 v65, v65
	v_exp_f32_e32 v66, v66
	v_exp_f32_e32 v67, v67
	v_exp_f32_e32 v68, v68
	v_exp_f32_e32 v69, v69
	v_add_f32_e32 v230, v65, v64
	v_exp_f32_e32 v70, v70
	v_add_f32_e32 v230, v66, v230
	v_exp_f32_e32 v71, v71
	v_add_f32_e32 v230, v67, v230
	v_exp_f32_e32 v72, v72
	v_add_f32_e32 v230, v68, v230
	v_exp_f32_e32 v73, v73
	v_add_f32_e32 v230, v69, v230
	v_exp_f32_e32 v74, v74
	v_add_f32_e32 v230, v70, v230
	v_exp_f32_e32 v75, v75
	v_add_f32_e32 v230, v71, v230
	v_exp_f32_e32 v76, v76
	v_add_f32_e32 v230, v72, v230
	v_exp_f32_e32 v77, v77
	v_add_f32_e32 v230, v73, v230
	v_exp_f32_e32 v78, v78
	v_add_f32_e32 v230, v74, v230
	v_exp_f32_e32 v79, v79
	v_add_f32_e32 v230, v75, v230
	v_add_f32_e32 v230, v76, v230
	v_add_f32_e32 v230, v77, v230
	v_add_f32_e32 v230, v78, v230
	v_add_f32_e32 v230, v79, v230
	v_add_f32_e32 v173, v173, v230
	v_cvt_pk_bf16_f32 v64, v64, v65
	v_cvt_pk_bf16_f32 v65, v66, v67
	v_cvt_pk_bf16_f32 v66, v68, v69
	v_cvt_pk_bf16_f32 v67, v70, v71
	v_cvt_pk_bf16_f32 v68, v72, v73
	v_cvt_pk_bf16_f32 v69, v74, v75
	v_cvt_pk_bf16_f32 v70, v76, v77
	v_cvt_pk_bf16_f32 v71, v78, v79
	s_waitcnt lgkmcnt(0)
	ds_read_b128 v[230:233], v252 offset:12416
	ds_read_b128 v[234:237], v253 offset:12416
	ds_read_b128 v[238:241], v250 offset:12544
	ds_read_b128 v[242:245], v251 offset:12544
	ds_read_b128 v[246:249], v252 offset:12544
	ds_read_b128 v[250:253], v253 offset:12544
	s_setprio 2
	v_mfma_f32_32x32x16_bf16 v[48:63], v[64:67], v[198:201], v[48:63]
	v_mfma_f32_32x32x16_bf16 v[32:47], v[64:67], v[206:209], v[32:47]
	v_mfma_f32_32x32x16_bf16 v[16:31], v[64:67], v[214:217], v[16:31]
	v_mfma_f32_32x32x16_bf16 v[0:15], v[64:67], v[222:225], v[0:15]
	v_mfma_f32_32x32x16_bf16 v[48:63], v[68:71], v[202:205], v[48:63]
	v_mfma_f32_32x32x16_bf16 v[32:47], v[68:71], v[210:213], v[32:47]
	v_mfma_f32_32x32x16_bf16 v[16:31], v[68:71], v[218:221], v[16:31]
	v_mfma_f32_32x32x16_bf16 v[0:15], v[68:71], v[226:229], v[0:15]
	s_waitcnt lgkmcnt(0)
; #define LAS __attribute__((address_space(3)))
; DI void expsum(f32x16& p, float& l_reg, bf16x8& pa0, bf16x8& pa1) {
; #pragma unroll
;     for (int r = 0; r < 16; ++r) p[r] = __builtin_amdgcn_exp2f(p[r]);
;     float ps = 0.f;
; #pragma unroll
;     for (int r = 0; r < 16; ++r) ps += p[r];
;     l_reg += ps; asm volatile("" : "+v"(l_reg));
;     ...
;     ATT_PK4(p, 0, pa0); ATT_PK4(p, 8, pa1);
;     ...
; }
; DI int v_rd_base(int lane) { return ((lane & 3) << 3) | (((lane >> 2) & 3) << 6) | (((lane >> 4) & 1) << 5) | (((lane >> 5) & 1) << 8); }
; template <int OFF> DI s16x4 tr_read(int vb) { s16x4 r; asm volatile("ds_read_b64_tr_b16 %0, %1 offset:%2" : "=&v"(r) : "v"(vb), "i"(OFF) : "memory"); return r; }
; template <int H> DI void v_reads(s16x4* vf, int vb) {
;     vf[0] = tr_read<v_rd_off(0, 2 * H, 0)>(vb); vf[1] = tr_read<v_rd_off(0, 2 * H, 1)>(vb); vf[2] = tr_read<v_rd_off(0, 2 * H + 1, 0)>(vb); vf[3] = tr_read<v_rd_off(0, 2 * H + 1, 1)>(vb);
;     vf[4] = tr_read<v_rd_off(1, 2 * H, 0)>(vb); vf[5] = tr_read<v_rd_off(1, 2 * H, 1)>(vb); vf[6] = tr_read<v_rd_off(1, 2 * H + 1, 0)>(vb); vf[7] = tr_read<v_rd_off(1, 2 * H + 1, 1)>(vb);
;     vf[8] = tr_read<v_rd_off(2, 2 * H, 0)>(vb); vf[9] = tr_read<v_rd_off(2, 2 * H, 1)>(vb); vf[10] = tr_read<v_rd_off(2, 2 * H + 1, 0)>(vb); vf[11] = tr_read<v_rd_off(2, 2 * H + 1, 1)>(vb);
;     vf[12] = tr_read<v_rd_off(3, 2 * H, 0)>(vb); vf[13] = tr_read<v_rd_off(3, 2 * H, 1)>(vb); vf[14] = tr_read<v_rd_off(3, 2 * H + 1, 0)>(vb); vf[15] = tr_read<v_rd_off(3, 2 * H + 1, 1)>(vb);
; }
; DI void pv_mma(f32x16* o, const s16x4* vf, bf16x8 pa0, bf16x8 pa1) {
;     ...
; #pragma unroll
;     for (int d0 = 0; d0 < 4; ++d0) {
;         o[d0] = __builtin_amdgcn_mfma_f32_32x32x16_bf16(pa0, ATT_PK(vf[4 * d0], vf[4 * d0 + 1]), o[d0], 0, 0, 0);
;         o[d0] = __builtin_amdgcn_mfma_f32_32x32x16_bf16(pa1, ATT_PK(vf[4 * d0 + 2], vf[4 * d0 + 3]), o[d0], 0, 0, 0); }
;     ...
; }
; template <int DQK, int D0A, int D0B> DI void k_reads(bf16x8* kf, const LAS unsigned char* Ks, int half, int r32, int hi) {
; #pragma unroll
;     for (int d0 = D0A; d0 < D0B; ++d0) kf[d0 - D0A] = *(const LAS bf16x8*)(Ks + half * (32 * DQK * 2) + kswz<DQK>(r32, (d0 * 16 + hi * 8) * 2));
; }
; template <int D0A, int D0B> DI void qk_mma(f32x16& p, const bf16x8* kf, const bf16x8* qr) {
; #pragma unroll
;     for (int d0 = D0A; d0 < D0B; ++d0) {
	v_mfma_f32_32x32x16_bf16 v[64:79], v[174:177], v[80:83], 0
	v_mfma_f32_32x32x16_bf16 v[64:79], v[178:181], v[84:87], v[64:79]
	v_mfma_f32_32x32x16_bf16 v[64:79], v[182:185], v[88:91], v[64:79]
	v_mfma_f32_32x32x16_bf16 v[64:79], v[186:189], v[92:95], v[64:79]
	v_mfma_f32_32x32x16_bf16 v[64:79], v[190:193], v[96:99], v[64:79]
	v_mfma_f32_32x32x16_bf16 v[64:79], v[194:197], v[100:103], v[64:79]
	v_mfma_f32_32x32x16_bf16 v[64:79], v[230:233], v[104:107], v[64:79]
	v_mfma_f32_32x32x16_bf16 v[64:79], v[234:237], v[108:111], v[64:79]
	v_mfma_f32_32x32x16_bf16 v[64:79], v[238:241], v[112:115], v[64:79]
	v_mfma_f32_32x32x16_bf16 v[64:79], v[242:245], v[116:119], v[64:79]
	v_mfma_f32_32x32x16_bf16 v[64:79], v[246:249], v[120:123], v[64:79]
	v_mfma_f32_32x32x16_bf16 v[64:79], v[250:253], v[124:127], v[64:79]
	s_setprio 0
	s_add_i32 s4, s43, -2
	s_and_b32 s4, s4, 3
	s_mulk_i32 s4, 0x6000
	v_add_u32_e32 v246, s4, v158
	v_add_u32_e32 v250, v246, v151
	v_add_u32_e32 v251, v246, v149
	v_add_u32_e32 v252, v246, v148
	v_add_u32_e32 v253, v246, v147
	ds_read_b128 v[190:193], v250 offset:128
	ds_read_b128 v[194:197], v251 offset:128
	ds_read_b128 v[174:177], v250
	ds_read_b128 v[178:181], v251
	ds_read_b128 v[182:185], v252
	ds_read_b128 v[186:189], v253
	ds_read_b64_tr_b16 v[198:199], v254 offset:0x2000
	ds_read_b64_tr_b16 v[200:201], v254 offset:0x2800
	ds_read_b64_tr_b16 v[202:203], v254 offset:0x3000
	ds_read_b64_tr_b16 v[204:205], v254 offset:0x3800
	ds_read_b64_tr_b16 v[206:207], v254 offset:0x2200
	ds_read_b64_tr_b16 v[208:209], v254 offset:0x2a00
	ds_read_b64_tr_b16 v[210:211], v254 offset:0x3200
	ds_read_b64_tr_b16 v[212:213], v254 offset:0x3a00
	ds_read_b64_tr_b16 v[214:215], v254 offset:0x2400
	ds_read_b64_tr_b16 v[216:217], v254 offset:0x2c00
	ds_read_b64_tr_b16 v[218:219], v254 offset:0x3400
	ds_read_b64_tr_b16 v[220:221], v254 offset:0x3c00
	ds_read_b64_tr_b16 v[222:223], v254 offset:0x2600
	ds_read_b64_tr_b16 v[224:225], v254 offset:0x2e00
	ds_read_b64_tr_b16 v[226:227], v254 offset:0x3600
	ds_read_b64_tr_b16 v[228:229], v254 offset:0x3e00
	s_setprio 1
	v_exp_f32_e32 v64, v64
	v_exp_f32_e32 v65, v65
	v_exp_f32_e32 v66, v66
	v_exp_f32_e32 v67, v67
	v_exp_f32_e32 v68, v68
	v_exp_f32_e32 v69, v69
	v_add_f32_e32 v230, v65, v64
	v_exp_f32_e32 v70, v70
	v_add_f32_e32 v230, v66, v230
	v_exp_f32_e32 v71, v71
	v_add_f32_e32 v230, v67, v230
	v_exp_f32_e32 v72, v72
	v_add_f32_e32 v230, v68, v230
	v_exp_f32_e32 v73, v73
	v_add_f32_e32 v230, v69, v230
	v_exp_f32_e32 v74, v74
	v_add_f32_e32 v230, v70, v230
	v_exp_f32_e32 v75, v75
	v_add_f32_e32 v230, v71, v230
	v_exp_f32_e32 v76, v76
	v_add_f32_e32 v230, v72, v230
	v_exp_f32_e32 v77, v77
	v_add_f32_e32 v230, v73, v230
	v_exp_f32_e32 v78, v78
	v_add_f32_e32 v230, v74, v230
	v_exp_f32_e32 v79, v79
	v_add_f32_e32 v230, v75, v230
	v_add_f32_e32 v230, v76, v230
	v_add_f32_e32 v230, v77, v230
	v_add_f32_e32 v230, v78, v230
	v_add_f32_e32 v230, v79, v230
	v_add_f32_e32 v173, v173, v230
	v_cvt_pk_bf16_f32 v64, v64, v65
	v_cvt_pk_bf16_f32 v65, v66, v67
	v_cvt_pk_bf16_f32 v66, v68, v69
	v_cvt_pk_bf16_f32 v67, v70, v71
	v_cvt_pk_bf16_f32 v68, v72, v73
	v_cvt_pk_bf16_f32 v69, v74, v75
	v_cvt_pk_bf16_f32 v70, v76, v77
	v_cvt_pk_bf16_f32 v71, v78, v79
	s_waitcnt lgkmcnt(0)
	ds_read_b128 v[230:233], v252 offset:128
	ds_read_b128 v[234:237], v253 offset:128
	ds_read_b128 v[238:241], v250 offset:256
	ds_read_b128 v[242:245], v251 offset:256
	ds_read_b128 v[246:249], v252 offset:256
	ds_read_b128 v[250:253], v253 offset:256
	s_setprio 2
	v_mfma_f32_32x32x16_bf16 v[48:63], v[64:67], v[198:201], v[48:63]
	v_mfma_f32_32x32x16_bf16 v[32:47], v[64:67], v[206:209], v[32:47]
	v_mfma_f32_32x32x16_bf16 v[16:31], v[64:67], v[214:217], v[16:31]
	v_mfma_f32_32x32x16_bf16 v[0:15], v[64:67], v[222:225], v[0:15]
	v_mfma_f32_32x32x16_bf16 v[48:63], v[68:71], v[202:205], v[48:63]
	v_mfma_f32_32x32x16_bf16 v[32:47], v[68:71], v[210:213], v[32:47]
	v_mfma_f32_32x32x16_bf16 v[16:31], v[68:71], v[218:221], v[16:31]
	v_mfma_f32_32x32x16_bf16 v[0:15], v[68:71], v[226:229], v[0:15]
	s_waitcnt lgkmcnt(0)
	v_mfma_f32_32x32x16_bf16 v[64:79], v[174:177], v[80:83], 0
	v_mfma_f32_32x32x16_bf16 v[64:79], v[178:181], v[84:87], v[64:79]
	v_mfma_f32_32x32x16_bf16 v[64:79], v[182:185], v[88:91], v[64:79]
	v_mfma_f32_32x32x16_bf16 v[64:79], v[186:189], v[92:95], v[64:79]
	v_mfma_f32_32x32x16_bf16 v[64:79], v[190:193], v[96:99], v[64:79]
	v_mfma_f32_32x32x16_bf16 v[64:79], v[194:197], v[100:103], v[64:79]
	v_mfma_f32_32x32x16_bf16 v[64:79], v[230:233], v[104:107], v[64:79]
	v_mfma_f32_32x32x16_bf16 v[64:79], v[234:237], v[108:111], v[64:79]
	v_mfma_f32_32x32x16_bf16 v[64:79], v[238:241], v[112:115], v[64:79]
	v_mfma_f32_32x32x16_bf16 v[64:79], v[242:245], v[116:119], v[64:79]
	v_mfma_f32_32x32x16_bf16 v[64:79], v[246:249], v[120:123], v[64:79]
	v_mfma_f32_32x32x16_bf16 v[64:79], v[250:253], v[124:127], v[64:79]
	s_add_i32 s43, s43, 1
	v_add_u32_e32 v136, s36, v136
	v_add_u32_e32 v138, s36, v138
	v_add_u32_e32 v140, s36, v140
	v_add_u32_e32 v142, s38, v142
	v_add_u32_e32 v144, s38, v144
	s_cmp_eq_u32 s43, 64
	s_mov_b32 s4, s0
	s_cbranch_scc0 .LBB0_1982
